# v56 + same unpack->v_fma_mix_f32 peephole on the remaining three A2 pairs and on the silu(z) blocks (3 pairs each)
# baseline (speedup 1.0000x reference)
.Lsz_do:
	ds_read_b128 v[20:23], v143
	ds_read_b128 v[24:27], v145
	ds_read_b128 v[28:31], v225
	s_waitcnt lgkmcnt(1)
	v_sub_f16_e32 v8, v24, v20
	v_sub_f16_sdwa v9, v24, v20 dst_sel:DWORD dst_unused:UNUSED_PAD src0_sel:WORD_1 src1_sel:WORD_1
	v_sub_f16_e32 v11, v25, v21
	v_sub_f16_sdwa v24, v25, v21 dst_sel:DWORD dst_unused:UNUSED_PAD src0_sel:WORD_1 src1_sel:WORD_1
	v_sub_f16_e32 v32, v27, v23
	v_sub_f16_sdwa v27, v27, v23 dst_sel:DWORD dst_unused:UNUSED_PAD src0_sel:WORD_1 src1_sel:WORD_1
	v_sub_f16_e32 v25, v26, v22
	v_sub_f16_sdwa v26, v26, v22 dst_sel:DWORD dst_unused:UNUSED_PAD src0_sel:WORD_1 src1_sel:WORD_1
	v_pack_b32_f16 v27, v32, v27
	v_pack_b32_f16 v11, v11, v24
	s_waitcnt lgkmcnt(0)
	v_pk_fma_f16 v31, v31, v27, v23
	v_pack_b32_f16 v23, v25, v26
	v_pk_fma_f16 v11, v29, v11, v21
	v_pk_fma_f16 v27, v30, v23, v22
	v_fma_mix_f32 v23, v11, s87, 0 op_sel_hi:[1,0,0]
	v_cvt_f32_f16_e32 v22, v11
	v_exp_f32_e32 v24, v23
	v_fma_mix_f32 v23, v11, s87, 0 op_sel:[1,0,0] op_sel_hi:[1,0,0]
	v_pack_b32_f16 v8, v8, v9
	v_exp_f32_e32 v25, v23
	v_cvt_f32_f16_sdwa v23, v11 dst_sel:DWORD dst_unused:UNUSED_PAD src0_sel:WORD_1
	v_add_f32_e32 v11, 1.0, v24
	v_rcp_f32_e32 v24, v11
	v_add_f32_e32 v11, 1.0, v25
	v_rcp_f32_e32 v25, v11
	v_fma_mix_f32 v11, v27, s87, 0 op_sel_hi:[1,0,0]
	v_pk_fma_f16 v9, v28, v8, v20
	v_exp_f32_e32 v11, v11
	v_fma_mix_f32 v28, v27, s87, 0 op_sel:[1,0,0] op_sel_hi:[1,0,0]
	v_fma_mix_f32 v20, v9, s87, 0 op_sel_hi:[1,0,0]
	v_exp_f32_e32 v29, v28
	v_add_f32_e32 v11, 1.0, v11
	v_rcp_f32_e32 v28, v11
	v_fma_mix_f32 v21, v9, s87, 0 op_sel:[1,0,0] op_sel_hi:[1,0,0]
	v_add_f32_e32 v11, 1.0, v29
	v_rcp_f32_e32 v29, v11
	v_fma_mix_f32 v11, v31, s87, 0 op_sel_hi:[1,0,0]
	v_fma_mix_f32 v32, v31, s87, 0 op_sel:[1,0,0] op_sel_hi:[1,0,0]
	v_exp_f32_e32 v11, v11
	v_exp_f32_e32 v20, v20
	v_exp_f32_e32 v21, v21
	v_exp_f32_e32 v33, v32
	v_add_f32_e32 v11, 1.0, v11
	v_add_f32_e32 v20, 1.0, v20
	v_add_f32_e32 v21, 1.0, v21
	v_rcp_f32_e32 v32, v11
	v_add_f32_e32 v11, 1.0, v33
	v_rcp_f32_e32 v20, v20
	v_rcp_f32_e32 v21, v21
	v_rcp_f32_e32 v33, v11
	v_fma_mix_f32 v8, v9, v20, 0 op_sel_hi:[1,0,0]
	v_fma_mix_f32 v9, v9, v21, 0 op_sel:[1,0,0] op_sel_hi:[1,0,0]
	v_pk_fma_f32 v[20:21], v[22:23], v[24:25], 0 op_sel_hi:[1,1,0]
	v_fma_mix_f32 v24, v27, v28, 0 op_sel_hi:[1,0,0]
	v_fma_mix_f32 v25, v27, v29, 0 op_sel:[1,0,0] op_sel_hi:[1,0,0]
	v_fma_mix_f32 v22, v31, v32, 0 op_sel_hi:[1,0,0]
	v_fma_mix_f32 v23, v31, v33, 0 op_sel:[1,0,0] op_sel_hi:[1,0,0]
	v_cvt_pk_f16_f32 v21, v20, v21
	v_cvt_pk_f16_f32 v23, v22, v23
	v_cvt_pk_f16_f32 v22, v24, v25
	v_cvt_pk_f16_f32 v20, v8, v9
	ds_write_b128 v146, v[20:23]

.LBB0_568:
	s_or_b64 exec, exec, s[34:35]
	v_exp_f32_e32 v24, v24
	v_exp_f32_e32 v20, v20
	v_exp_f32_e32 v21, v21
	v_or_b32_e32 v40, 28, v9
	v_fmamk_f32 v24, v24, 0xbf92477c, v147
	v_rcp_f32_e32 v24, v24
	v_add_f32_e32 v20, 1.0, v20
	v_rcp_f32_e32 v36, v20
	v_add_f32_e32 v21, 1.0, v21
	v_add_f32_dpp v20, v24, v24 row_shr:1 row_mask:0xf bank_mask:0xf bound_ctrl:1
	v_rcp_f32_e32 v37, v21
	v_add_u32_e32 v32, s38, v124
	v_add_f32_dpp v20, v20, v20 row_shr:2 row_mask:0xf bank_mask:0xf bound_ctrl:1
	ds_read_b128 v[28:31], v32 offset:1280
	ds_read_b128 v[32:35], v32 offset:4864
	v_add_f32_dpp v20, v20, v20 row_shr:4 row_mask:0xf bank_mask:0xf bound_ctrl:1
	s_nop 1
	v_add_f32_dpp v41, v20, v20 row_shr:8 row_mask:0xf bank_mask:0xf bound_ctrl:1
	v_exp_f32_e32 v20, v25
	v_sub_f32_e32 v42, v41, v24
	ds_bpermute_b32 v24, v40, v41
	s_waitcnt lgkmcnt(1)
	v_pk_fma_f32 v[28:29], v[36:37], v[28:29], v[32:33]
	v_fmamk_f32 v20, v20, 0xbf92477c, v147
	v_rcp_f32_e32 v20, v20
	v_fma_mix_f32 v28, v70, v28, 0 op_sel_hi:[1,0,0]
	v_fma_mix_f32 v29, v70, v29, 0 op_sel:[1,0,0] op_sel_hi:[1,0,0]
	s_nop 0
	v_add_f32_dpp v21, v20, v20 row_shr:1 row_mask:0xf bank_mask:0xf bound_ctrl:1
	s_nop 1
	v_add_f32_dpp v21, v21, v21 row_shr:2 row_mask:0xf bank_mask:0xf bound_ctrl:1
	v_mov_b32_e32 v9, v8
	s_nop 0
	v_add_f32_dpp v21, v21, v21 row_shr:4 row_mask:0xf bank_mask:0xf bound_ctrl:1
	v_fma_mix_f32 v32, v72, v8, 0 op_sel_hi:[1,0,0]
	v_fma_mix_f32 v33, v72, v9, 0 op_sel:[1,0,0] op_sel_hi:[1,0,0]
	v_add_f32_dpp v43, v21, v21 row_shr:8 row_mask:0xf bank_mask:0xf bound_ctrl:1
	v_sub_f32_e32 v87, v43, v20
	v_exp_f32_e32 v20, v26
	v_exp_f32_e32 v21, v22
	ds_bpermute_b32 v25, v40, v43
	v_fmamk_f32 v20, v20, 0xbf92477c, v147
	v_rcp_f32_e32 v20, v20
	v_add_f32_e32 v21, 1.0, v21
	v_rcp_f32_e32 v38, v21
	s_nop 0
	v_add_f32_dpp v21, v20, v20 row_shr:1 row_mask:0xf bank_mask:0xf bound_ctrl:1
	s_nop 1
	v_add_f32_dpp v21, v21, v21 row_shr:2 row_mask:0xf bank_mask:0xf bound_ctrl:1
	s_nop 1
	v_add_f32_dpp v21, v21, v21 row_shr:4 row_mask:0xf bank_mask:0xf bound_ctrl:1
	s_nop 1
	v_add_f32_dpp v162, v21, v21 row_shr:8 row_mask:0xf bank_mask:0xf bound_ctrl:1
	v_sub_f32_e32 v163, v162, v20
	v_exp_f32_e32 v20, v27
	v_exp_f32_e32 v21, v23
	ds_bpermute_b32 v26, v40, v162
	ds_bpermute_b32 v22, v157, v162
	v_fmamk_f32 v20, v20, 0xbf92477c, v147
	v_rcp_f32_e32 v20, v20
	v_add_f32_e32 v21, 1.0, v21
	v_rcp_f32_e32 v39, v21
	s_nop 0
	v_add_f32_dpp v21, v20, v20 row_shr:1 row_mask:0xf bank_mask:0xf bound_ctrl:1
	v_pk_fma_f32 v[30:31], v[38:39], v[30:31], v[34:35]
	s_nop 0
	v_add_f32_dpp v21, v21, v21 row_shr:2 row_mask:0xf bank_mask:0xf bound_ctrl:1
	s_nop 1
	v_add_f32_dpp v21, v21, v21 row_shr:4 row_mask:0xf bank_mask:0xf bound_ctrl:1
	v_fma_mix_f32 v8, v73, v8, 0 op_sel_hi:[1,0,0]
	v_fma_mix_f32 v9, v73, v9, 0 op_sel:[1,0,0] op_sel_hi:[1,0,0]
	v_add_f32_dpp v165, v21, v21 row_shr:8 row_mask:0xf bank_mask:0xf bound_ctrl:1
	ds_bpermute_b32 v27, v40, v165
	v_sub_f32_e32 v166, v165, v20
	ds_bpermute_b32 v20, v157, v41
	ds_bpermute_b32 v21, v157, v43
	ds_bpermute_b32 v23, v157, v165
	s_waitcnt lgkmcnt(5)
	v_sub_f32_e32 v157, v163, v26
	v_exp_f32_e32 v160, v157
	v_sub_f32_e32 v157, v162, v26
	v_exp_f32_e32 v162, v157
	s_waitcnt lgkmcnt(3)
	v_sub_f32_e32 v157, v166, v27
	v_sub_f32_e32 v41, v41, v24
	v_sub_f32_e32 v43, v43, v25
	v_exp_f32_e32 v161, v157
	v_sub_f32_e32 v157, v165, v27
	v_sub_f32_e32 v40, v42, v24
	v_exp_f32_e32 v42, v41
	v_exp_f32_e32 v43, v43
	v_exp_f32_e32 v163, v157
	v_sub_f32_e32 v41, v87, v25
	v_exp_f32_e32 v40, v40
	v_exp_f32_e32 v41, v41
	v_rcp_f32_e32 v86, v42
	v_rcp_f32_e32 v87, v43
	v_rcp_f32_e32 v164, v162
	v_rcp_f32_e32 v165, v163
	v_fma_mix_f32 v42, v78, v42, 0 op_sel_hi:[1,0,0]
	v_fma_mix_f32 v43, v78, v43, 0 op_sel:[1,0,0] op_sel_hi:[1,0,0]
	v_fma_mix_f32 v158, v79, v162, 0 op_sel_hi:[1,0,0]
	v_fma_mix_f32 v159, v79, v163, 0 op_sel:[1,0,0] op_sel_hi:[1,0,0]
	v_pk_mul_f32 v[34:35], v[32:33], v[40:41]
	v_pk_mul_f32 v[40:41], v[8:9], v[160:161]
	v_pk_mul_f32 v[32:33], v[36:37], v[32:33]
	v_pk_mul_f32 v[8:9], v[38:39], v[8:9]
	v_fma_mix_f32 v30, v71, v30, 0 op_sel_hi:[1,0,0]
	v_fma_mix_f32 v31, v71, v31, 0 op_sel:[1,0,0] op_sel_hi:[1,0,0]
	v_pk_mul_f32 v[32:33], v[32:33], v[86:87]
	v_pk_mul_f32 v[8:9], v[8:9], v[164:165]
	v_pk_mul_f32 v[36:37], v[28:29], v[86:87]
	v_pk_mul_f32 v[38:39], v[30:31], v[164:165]
	v_add_u32_e32 v86, s71, v114
	v_cvt_pk_f16_f32 v9, v8, v9
	v_cvt_pk_f16_f32 v8, v32, v33
	v_cvt_pk_f16_f32 v41, v40, v41
	v_cvt_pk_f16_f32 v40, v34, v35
	v_cvt_pk_f16_f32 v35, v158, v159
	v_cvt_pk_f16_f32 v34, v42, v43
	ds_write_b64 v86, v[8:9] offset:4608
	v_cvt_pk_f16_f32 v9, v38, v39
	v_cvt_pk_f16_f32 v8, v36, v37
	ds_write_b64 v86, v[40:41]
	ds_write_b64 v86, v[34:35] offset:2304
	ds_write_b64 v86, v[8:9] offset:6912
	s_waitcnt lgkmcnt(4)
	s_and_saveexec_b64 s[34:35], s[4:5]
	s_cbranch_execz .LBB0_570
	v_add_u32_e32 v8, s71, v124
	ds_write_b128 v8, v[24:27] offset:13568
	ds_write_b128 v8, v[20:23] offset:13824

.Lds_early:
	s_and_b64 vcc, exec, s[36:37]
	s_cbranch_vccnz .LBB0_581
	s_and_b64 vcc, exec, s[56:57]
	s_cbranch_vccnz .Lsz_skip
	v_add_u32_e32 v34, 0xfffff000, v143
	v_add_u32_e32 v35, 0xfffff000, v145
	ds_read_b128 v[20:23], v34
	ds_read_b128 v[24:27], v35
	ds_read_b128 v[28:31], v225
	s_waitcnt lgkmcnt(1)
	v_sub_f16_e32 v8, v24, v20
	v_sub_f16_sdwa v9, v24, v20 dst_sel:DWORD dst_unused:UNUSED_PAD src0_sel:WORD_1 src1_sel:WORD_1
	v_sub_f16_e32 v11, v25, v21
	v_sub_f16_sdwa v24, v25, v21 dst_sel:DWORD dst_unused:UNUSED_PAD src0_sel:WORD_1 src1_sel:WORD_1
	v_sub_f16_e32 v32, v27, v23
	v_sub_f16_sdwa v27, v27, v23 dst_sel:DWORD dst_unused:UNUSED_PAD src0_sel:WORD_1 src1_sel:WORD_1
	v_sub_f16_e32 v25, v26, v22
	v_sub_f16_sdwa v26, v26, v22 dst_sel:DWORD dst_unused:UNUSED_PAD src0_sel:WORD_1 src1_sel:WORD_1
	v_pack_b32_f16 v27, v32, v27
	v_pack_b32_f16 v11, v11, v24
	s_waitcnt lgkmcnt(0)
	v_pk_fma_f16 v31, v31, v27, v23
	v_pack_b32_f16 v23, v25, v26
	v_pk_fma_f16 v11, v29, v11, v21
	v_pk_fma_f16 v27, v30, v23, v22
	v_fma_mix_f32 v23, v11, s87, 0 op_sel_hi:[1,0,0]
	v_cvt_f32_f16_e32 v22, v11
	v_exp_f32_e32 v24, v23
	v_fma_mix_f32 v23, v11, s87, 0 op_sel:[1,0,0] op_sel_hi:[1,0,0]
	v_pack_b32_f16 v8, v8, v9
	v_exp_f32_e32 v25, v23
	v_cvt_f32_f16_sdwa v23, v11 dst_sel:DWORD dst_unused:UNUSED_PAD src0_sel:WORD_1
	v_add_f32_e32 v11, 1.0, v24
	v_rcp_f32_e32 v24, v11
	v_add_f32_e32 v11, 1.0, v25
	v_rcp_f32_e32 v25, v11
	v_fma_mix_f32 v11, v27, s87, 0 op_sel_hi:[1,0,0]
	v_pk_fma_f16 v9, v28, v8, v20
	v_exp_f32_e32 v11, v11
	v_fma_mix_f32 v28, v27, s87, 0 op_sel:[1,0,0] op_sel_hi:[1,0,0]
	v_fma_mix_f32 v20, v9, s87, 0 op_sel_hi:[1,0,0]
	v_exp_f32_e32 v29, v28
	v_add_f32_e32 v11, 1.0, v11
	v_rcp_f32_e32 v28, v11
	v_fma_mix_f32 v21, v9, s87, 0 op_sel:[1,0,0] op_sel_hi:[1,0,0]
	v_add_f32_e32 v11, 1.0, v29
	v_rcp_f32_e32 v29, v11
	v_fma_mix_f32 v11, v31, s87, 0 op_sel_hi:[1,0,0]
	v_fma_mix_f32 v32, v31, s87, 0 op_sel:[1,0,0] op_sel_hi:[1,0,0]
	v_exp_f32_e32 v11, v11
	v_exp_f32_e32 v20, v20
	v_exp_f32_e32 v21, v21
	v_exp_f32_e32 v33, v32
	v_add_f32_e32 v11, 1.0, v11
	v_add_f32_e32 v20, 1.0, v20
	v_add_f32_e32 v21, 1.0, v21
	v_rcp_f32_e32 v32, v11
	v_add_f32_e32 v11, 1.0, v33
	v_rcp_f32_e32 v20, v20
	v_rcp_f32_e32 v21, v21
	v_rcp_f32_e32 v33, v11
	v_fma_mix_f32 v8, v9, v20, 0 op_sel_hi:[1,0,0]
	v_fma_mix_f32 v9, v9, v21, 0 op_sel:[1,0,0] op_sel_hi:[1,0,0]
	v_pk_fma_f32 v[20:21], v[22:23], v[24:25], 0 op_sel_hi:[1,1,0]
	v_fma_mix_f32 v24, v27, v28, 0 op_sel_hi:[1,0,0]
	v_fma_mix_f32 v25, v27, v29, 0 op_sel:[1,0,0] op_sel_hi:[1,0,0]
	v_fma_mix_f32 v22, v31, v32, 0 op_sel_hi:[1,0,0]
	v_fma_mix_f32 v23, v31, v33, 0 op_sel:[1,0,0] op_sel_hi:[1,0,0]
	v_cvt_pk_f16_f32 v245, v20, v21
	v_cvt_pk_f16_f32 v247, v22, v23
	v_cvt_pk_f16_f32 v246, v24, v25
	v_cvt_pk_f16_f32 v244, v8, v9
